# v94 + mLSTM scan staging: direction-dependent 8-element reversal done with one v_perm_b32 per dword (uniform selector) instead of v_alignbit + v_cndmask
# baseline (speedup 1.0000x reference)
.LBB0_208:
	s_waitcnt lgkmcnt(0)
	s_barrier
	s_mov_b32 s98, 0x05040706
	s_cmp_lg_u64 s[2:3], 0
	s_cselect_b32 s98, 0x03020100, s98
	s_waitcnt vmcnt(13)
	ds_write_b128 v189, v[0:3]
	s_waitcnt vmcnt(12)
	ds_write_b128 v189, v[4:7] offset:34816
	s_waitcnt vmcnt(11)
	v_perm_b32 v80, v8, v11, s98
	v_perm_b32 v81, v9, v10, s98
	ds_read_b128 v[72:75], v156
	v_perm_b32 v83, v11, v8, s98
	v_lshlrev_b32_e32 v84, 16, v83
	v_and_b32_e32 v83, 0xffff0000, v83
	v_perm_b32 v82, v10, v9, s98
	ds_read_b128 v[76:79], v156 offset:16
	ds_read_b128 v[246:249], v156
	ds_read_b128 v[250:253], v156 offset:16
	s_waitcnt lgkmcnt(1)
	v_mul_f32_e32 v72, v72, v84
	v_mul_f32_e32 v73, v73, v83
	v_cvt_pk_bf16_f32 v72, v72, v73
	v_lshlrev_b32_e32 v73, 16, v82
	v_mul_f32_e32 v73, v74, v73
	v_and_b32_e32 v74, 0xffff0000, v82
	v_mul_f32_e32 v74, v75, v74
	v_cvt_pk_bf16_f32 v73, v73, v74
	v_lshlrev_b32_e32 v74, 16, v81
	v_and_b32_e32 v75, 0xffff0000, v81
	s_waitcnt lgkmcnt(0)
	v_mul_f32_e32 v74, v76, v74
	v_mul_f32_e32 v75, v77, v75
	v_cvt_pk_bf16_f32 v74, v74, v75
	v_lshlrev_b32_e32 v75, 16, v80
	v_mul_f32_e32 v75, v78, v75
	v_and_b32_e32 v76, 0xffff0000, v80
	v_mul_f32_e32 v76, v79, v76
	v_cvt_pk_bf16_f32 v75, v75, v76
	ds_write_b128 v190, v[72:75]
	s_waitcnt vmcnt(10)
	ds_write_b128 v192, v[12:15]
	s_waitcnt vmcnt(9)
	ds_write_b128 v192, v[16:19] offset:34816
	s_waitcnt vmcnt(8)
	v_perm_b32 v80, v20, v23, s98
	v_perm_b32 v81, v21, v22, s98
	v_perm_b32 v83, v23, v20, s98
	v_lshlrev_b32_e32 v84, 16, v83
	v_and_b32_e32 v83, 0xffff0000, v83
	v_perm_b32 v82, v22, v21, s98
	v_mul_f32_e32 v72, v246, v84
	v_mul_f32_e32 v73, v247, v83
	v_cvt_pk_bf16_f32 v72, v72, v73
	v_lshlrev_b32_e32 v73, 16, v82
	v_mul_f32_e32 v73, v248, v73
	v_and_b32_e32 v74, 0xffff0000, v82
	v_mul_f32_e32 v74, v249, v74
	v_cvt_pk_bf16_f32 v73, v73, v74
	v_lshlrev_b32_e32 v74, 16, v81
	v_and_b32_e32 v75, 0xffff0000, v81
	v_mul_f32_e32 v74, v250, v74
	v_mul_f32_e32 v75, v251, v75
	v_cvt_pk_bf16_f32 v74, v74, v75
	v_lshlrev_b32_e32 v75, 16, v80
	v_mul_f32_e32 v75, v252, v75
	v_and_b32_e32 v76, 0xffff0000, v80
	v_mul_f32_e32 v76, v253, v76
	v_cvt_pk_bf16_f32 v75, v75, v76
	ds_write_b128 v193, v[72:75]
	s_waitcnt vmcnt(7)
	ds_write_b128 v194, v[24:27]
	s_waitcnt vmcnt(6)
	ds_write_b128 v194, v[28:31] offset:34816
	s_waitcnt vmcnt(5)
	v_perm_b32 v80, v32, v35, s98
	v_perm_b32 v81, v33, v34, s98
	v_perm_b32 v83, v35, v32, s98
	v_lshlrev_b32_e32 v84, 16, v83
	v_and_b32_e32 v83, 0xffff0000, v83
	v_perm_b32 v82, v34, v33, s98
	v_mul_f32_e32 v72, v246, v84
	v_mul_f32_e32 v73, v247, v83
	v_cvt_pk_bf16_f32 v72, v72, v73
	v_lshlrev_b32_e32 v73, 16, v82
	v_mul_f32_e32 v73, v248, v73
	v_and_b32_e32 v74, 0xffff0000, v82
	v_mul_f32_e32 v74, v249, v74
	v_cvt_pk_bf16_f32 v73, v73, v74
	v_lshlrev_b32_e32 v74, 16, v81
	v_and_b32_e32 v75, 0xffff0000, v81
	v_mul_f32_e32 v74, v250, v74
	v_mul_f32_e32 v75, v251, v75
	v_cvt_pk_bf16_f32 v74, v74, v75
	v_lshlrev_b32_e32 v75, 16, v80
	v_mul_f32_e32 v75, v252, v75
	v_and_b32_e32 v76, 0xffff0000, v80
	v_mul_f32_e32 v76, v253, v76
	v_cvt_pk_bf16_f32 v75, v75, v76
	ds_write_b128 v195, v[72:75]
	s_waitcnt vmcnt(4)
	ds_write_b128 v196, v[36:39]
	s_waitcnt vmcnt(3)
	ds_write_b128 v196, v[40:43] offset:34816
	s_waitcnt vmcnt(2)
	v_perm_b32 v80, v44, v47, s98
	v_perm_b32 v81, v45, v46, s98
	v_perm_b32 v83, v47, v44, s98
	v_lshlrev_b32_e32 v84, 16, v83
	v_and_b32_e32 v83, 0xffff0000, v83
	v_perm_b32 v82, v46, v45, s98
	v_mul_f32_e32 v72, v246, v84
	v_mul_f32_e32 v73, v247, v83
	v_cvt_pk_bf16_f32 v72, v72, v73
	v_lshlrev_b32_e32 v73, 16, v82
	v_mul_f32_e32 v73, v248, v73
	v_and_b32_e32 v74, 0xffff0000, v82
	v_mul_f32_e32 v74, v249, v74
	v_cvt_pk_bf16_f32 v73, v73, v74
	v_lshlrev_b32_e32 v74, 16, v81
	v_and_b32_e32 v75, 0xffff0000, v81
	v_mul_f32_e32 v74, v250, v74
	v_mul_f32_e32 v75, v251, v75
	v_cvt_pk_bf16_f32 v74, v74, v75
	v_lshlrev_b32_e32 v75, 16, v80
	v_mul_f32_e32 v75, v252, v75
	v_and_b32_e32 v76, 0xffff0000, v80
	v_mul_f32_e32 v76, v253, v76
	v_cvt_pk_bf16_f32 v75, v75, v76
	ds_write_b128 v197, v[72:75]
	s_waitcnt vmcnt(1)
	v_perm_b32 v75, v48, v51, s98
	v_perm_b32 v74, v49, v50, s98
	v_perm_b32 v73, v50, v49, s98
	v_perm_b32 v72, v51, v48, s98
	v_add_u32_e32 v76, v168, v188
	ds_write_b128 v76, v[72:75]
	s_waitcnt vmcnt(0)
	v_perm_b32 v75, v52, v55, s98
	v_perm_b32 v74, v53, v54, s98
	v_perm_b32 v73, v54, v53, s98
	v_perm_b32 v72, v55, v52, s98
	v_add_u32_e32 v76, v168, v191
	v_mov_b32_e32 v88, 0
	ds_write_b128 v76, v[72:75]
	s_mov_b32 s85, 0
	v_mov_b32_e32 v89, v88
	v_mov_b32_e32 v90, v88
	v_mov_b32_e32 v91, v88
	v_mov_b32_e32 v92, v88
	v_mov_b32_e32 v93, v88
	v_mov_b32_e32 v94, v88
	v_mov_b32_e32 v95, v88
	v_mov_b32_e32 v100, v88
	v_mov_b32_e32 v101, v88
	v_mov_b32_e32 v102, v88
	v_mov_b32_e32 v103, v88
	v_mov_b32_e32 v108, v88
	v_mov_b32_e32 v109, v88
	v_mov_b32_e32 v110, v88
	v_mov_b32_e32 v111, v88
	v_mov_b32_e32 v96, v88
	v_mov_b32_e32 v97, v88
	v_mov_b32_e32 v98, v88
	v_mov_b32_e32 v99, v88
	v_mov_b32_e32 v104, v88
	v_mov_b32_e32 v105, v88
	v_mov_b32_e32 v106, v88
	v_mov_b32_e32 v107, v88
	v_mov_b32_e32 v112, v88
	v_mov_b32_e32 v113, v88
	v_mov_b32_e32 v114, v88
	v_mov_b32_e32 v115, v88
	v_mov_b32_e32 v116, v88
	v_mov_b32_e32 v117, v88
	v_mov_b32_e32 v118, v88
	v_mov_b32_e32 v119, v88
	v_mov_b32_e32 v72, v88
	v_mov_b32_e32 v73, v88
	v_mov_b32_e32 v74, v88
	v_mov_b32_e32 v75, v88
	v_mov_b32_e32 v76, v88
	v_mov_b32_e32 v77, v88
	v_mov_b32_e32 v78, v88
	v_mov_b32_e32 v79, v88
	v_mov_b32_e32 v80, v88
	v_mov_b32_e32 v81, v88
	v_mov_b32_e32 v82, v88
	v_mov_b32_e32 v83, v88
	v_mov_b32_e32 v84, v88
	v_mov_b32_e32 v85, v88
	v_mov_b32_e32 v86, v88
	v_mov_b32_e32 v87, v88
	s_waitcnt lgkmcnt(0)
	s_barrier
	s_add_i32 s99, s84, 1
	s_cmp_ge_u32 s99, s95
	s_cbranch_scc1 .Lpf_skip
	s_lshl_b32 s100, s99, 7
	s_sub_i32 s101, s94, s100
	s_and_b64 s[86:87], s[2:3], exec
	s_cselect_b32 s100, s100, s101
	s_add_i32 s100, s100, s89
	s_ashr_i32 s101, s100, 7
	v_add_u32_e32 v0, s100, v148
	v_add_u32_e32 v12, s100, v150
	v_add_u32_e32 v24, s100, v151
	v_add_u32_e32 v36, s100, v152
	v_ashrrev_i32_e32 v1, 31, v0
	v_mad_i64_i32 v[8:9], s[86:87], s101, v149, v[136:137]
	v_ashrrev_i32_e32 v13, 31, v12
	v_mad_i64_i32 v[20:21], s[86:87], s101, v149, v[138:139]
	v_ashrrev_i32_e32 v25, 31, v24
	v_mad_i64_i32 v[32:33], s[86:87], s101, v149, v[140:141]
	v_ashrrev_i32_e32 v37, 31, v36
	v_mad_i64_i32 v[46:47], s[86:87], s101, v149, v[142:143]
	v_lshlrev_b64 v[0:1], 8, v[0:1]
	v_lshlrev_b64 v[44:45], 8, v[8:9]
	v_lshlrev_b64 v[12:13], 8, v[12:13]
	v_lshlrev_b64 v[52:53], 8, v[20:21]
	v_lshlrev_b64 v[24:25], 8, v[24:25]
	v_lshlrev_b64 v[32:33], 8, v[32:33]
	v_lshlrev_b64 v[36:37], 8, v[36:37]
	v_lshlrev_b64 v[46:47], 8, v[46:47]
	v_lshl_add_u64 v[2:3], v[128:129], 0, v[0:1]
	v_lshl_add_u64 v[4:5], v[130:131], 0, v[0:1]
	v_lshl_add_u64 v[8:9], v[132:133], 0, v[44:45]
	v_lshl_add_u64 v[14:15], v[128:129], 0, v[12:13]
	v_lshl_add_u64 v[16:17], v[130:131], 0, v[12:13]
	v_lshl_add_u64 v[20:21], v[132:133], 0, v[52:53]
	v_lshl_add_u64 v[26:27], v[128:129], 0, v[24:25]
	v_lshl_add_u64 v[28:29], v[130:131], 0, v[24:25]
	v_lshl_add_u64 v[32:33], v[132:133], 0, v[32:33]
	v_lshl_add_u64 v[38:39], v[128:129], 0, v[36:37]
	v_lshl_add_u64 v[40:41], v[130:131], 0, v[36:37]
	v_lshl_add_u64 v[46:47], v[132:133], 0, v[46:47]
	v_lshl_add_u64 v[48:49], v[144:145], 0, v[44:45]
	v_lshl_add_u64 v[52:53], v[144:145], 0, v[52:53]
	global_load_dwordx4 v[0:3], v[2:3], off
	s_nop 0
	global_load_dwordx4 v[4:7], v[4:5], off
	s_nop 0
	global_load_dwordx4 v[8:11], v[8:9], off
	s_nop 0
	global_load_dwordx4 v[12:15], v[14:15], off
	s_nop 0
	global_load_dwordx4 v[16:19], v[16:17], off
	s_nop 0
	global_load_dwordx4 v[20:23], v[20:21], off
	s_nop 0
	global_load_dwordx4 v[24:27], v[26:27], off
	s_nop 0
	global_load_dwordx4 v[28:31], v[28:29], off
	s_nop 0
	global_load_dwordx4 v[32:35], v[32:33], off
	s_nop 0
	global_load_dwordx4 v[36:39], v[38:39], off
	s_nop 0
	global_load_dwordx4 v[40:43], v[40:41], off
	s_nop 0
	global_load_dwordx4 v[44:47], v[46:47], off
	s_nop 0
	global_load_dwordx4 v[48:51], v[48:49], off
	s_nop 0
	global_load_dwordx4 v[52:55], v[52:53], off
	s_and_saveexec_b64 s[86:87], s[0:1]
	s_cbranch_execz .Lpf_215
	v_add_u32_e32 v120, s100, v153
	s_waitcnt lgkmcnt(0)
	v_ashrrev_i32_e32 v121, 31, v120
	v_readlane_b32 s100, v255, 10
	v_lshlrev_b64 v[120:121], 6, v[120:121]
	v_readlane_b32 s101, v255, 11
	s_nop 1
	v_lshl_add_u64 v[120:121], s[100:101], 0, v[120:121]
	global_load_dword v154, v[120:121], off
	global_load_dword v155, v[120:121], off offset:16
